# on top of the decode fast path: RG-LRU unit prologue gate-weight loads issued together, conversion loop waits only for the item it consumes
# speedup vs baseline: 1.0028x; 1.0025x over previous
; __device__ __forceinline__ unsigned pk4_fp8(float a, float b, float c, float d) { int w = 0; w = __builtin_amdgcn_cvt_pk_fp8_f32(a, b, w, false); w = __builtin_amdgcn_cvt_pk_fp8_f32(c, d, w, true); return (unsigned)w; }
; #define GAS __attribute__((address_space(1)))
; #define LAS __attribute__((address_space(3)))
; #define LDS_WAIT() asm volatile("s_waitcnt lgkmcnt(0)" ::: "memory")
; __device__ __forceinline__ unsigned pk4_fp8(float a, float b, float c, float d) { int w = 0; w = __builtin_amdgcn_cvt_pk_fp8_f32(a, b, w, false); w = __builtin_amdgcn_cvt_pk_fp8_f32(c, d, w, true); return (unsigned)w; }
; __device__ __forceinline__ void cvt_store(const CvtItem& c, const f32x4 (&v)[8], LAS float* scr, int lane) {
; #pragma unroll
;     for (int i = 0; i < 8; ++i) { const int kk = 4 * i + (lane >> 4); LAS float* p = scr + kk * 65 + 4 * (lane & 15); p[0] = v[i][0]; p[1] = v[i][1]; p[2] = v[i][2]; p[3] = v[i][3]; }
;     LDS_WAIT(); asm volatile("" ::: "memory");
;     if (c.f8) {
; #pragma unroll
;         for (int j = 0; j < 2; ++j) { const int idx = lane + 64 * j, n = idx >> 1, cc = idx & 1; const LAS float* s = scr + (16 * cc) * 65 + n;
;             v4u o; o.x = pk4_fp8(s[0 * 65] * F8_SW, s[1 * 65] * F8_SW, s[2 * 65] * F8_SW, s[3 * 65] * F8_SW); o.y = pk4_fp8(s[4 * 65] * F8_SW, s[5 * 65] * F8_SW, s[6 * 65] * F8_SW, s[7 * 65] * F8_SW);
;             o.z = pk4_fp8(s[8 * 65] * F8_SW, s[9 * 65] * F8_SW, s[10 * 65] * F8_SW, s[11 * 65] * F8_SW); o.w = pk4_fp8(s[12 * 65] * F8_SW, s[13 * 65] * F8_SW, s[14 * 65] * F8_SW, s[15 * 65] * F8_SW);
;             *(GAS v4u*)(c.dst + (size_t)n * D + 16 * cc) = o; }
.LBB0_536:
	ds_write2_b32 v105, v34, v35 offset1:1
	ds_write2_b32 v105, v36, v37 offset0:2 offset1:3
	v_add_u32_e32 v34, 0x410, v105
	ds_write2_b32 v34, v38, v39 offset1:1
	v_add_u32_e32 v34, 0x418, v105
	ds_write2_b32 v34, v40, v41 offset1:1
	v_add_u32_e32 v34, 0x820, v105
	ds_write2_b32 v34, v42, v43 offset1:1
	v_add_u32_e32 v34, 0x828, v105
	ds_write2_b32 v34, v44, v45 offset1:1
	v_add_u32_e32 v34, 0xc30, v105
	ds_write2_b32 v34, v46, v47 offset1:1
	v_add_u32_e32 v34, 0xc38, v105
	ds_write2_b32 v34, v48, v49 offset1:1
	v_add_u32_e32 v34, 0x1040, v105
	ds_write2_b32 v34, v50, v51 offset1:1
	v_add_u32_e32 v34, 0x1048, v105
	ds_write2_b32 v34, v52, v53 offset1:1
	v_add_u32_e32 v34, 0x1450, v105
	ds_write2_b32 v34, v54, v55 offset1:1
	v_add_u32_e32 v34, 0x1458, v105
	ds_write2_b32 v34, v56, v57 offset1:1
	v_add_u32_e32 v34, 0x1860, v105
	ds_write2_b32 v34, v58, v59 offset1:1
	v_add_u32_e32 v34, 0x1868, v105
	ds_write2_b32 v34, v60, v61 offset1:1
	v_add_u32_e32 v34, 0x1c70, v105
	ds_write2_b32 v34, v62, v63 offset1:1
	v_add_u32_e32 v34, 0x1c78, v105
	ds_write2_b32 v34, v64, v65 offset1:1
	s_waitcnt lgkmcnt(0)
	s_cmp_eq_u32 s34, 0
	s_cbranch_scc1 .LBB0_538
	ds_read2_b32 v[34:35], v81 offset1:65
	s_mov_b64 s[42:43], 0
	s_waitcnt lgkmcnt(0)
	v_mul_f32_e32 v36, 0x42800000, v34
	v_mul_f32_e32 v37, 0x42800000, v35
	ds_read2_b32 v[34:35], v81 offset0:130 offset1:195
	s_waitcnt lgkmcnt(0)
	v_mul_f32_e32 v38, 0x42800000, v34
	v_cvt_pk_fp8_f32 v34, v36, v37
	v_mul_f32_e32 v35, 0x42800000, v35
	v_cvt_pk_fp8_f32 v34, v38, v35 op_sel:[0,0,1]
	v_add_u32_e32 v35, 0x400, v81
	ds_read2_b32 v[36:37], v35 offset0:4 offset1:69
	s_waitcnt lgkmcnt(0)
	v_mul_f32_e32 v38, 0x42800000, v36
	v_mul_f32_e32 v39, 0x42800000, v37
	ds_read2_b32 v[36:37], v35 offset0:134 offset1:199
	v_cvt_pk_fp8_f32 v35, v38, v39
	v_add_u32_e32 v38, 0x800, v81
	s_waitcnt lgkmcnt(0)
	v_mul_f32_e32 v36, 0x42800000, v36
	v_mul_f32_e32 v37, 0x42800000, v37
	v_cvt_pk_fp8_f32 v35, v36, v37 op_sel:[0,0,1]
	ds_read2_b32 v[36:37], v38 offset0:8 offset1:73
	s_waitcnt lgkmcnt(0)
	v_mul_f32_e32 v39, 0x42800000, v36
	v_mul_f32_e32 v40, 0x42800000, v37
	ds_read2_b32 v[36:37], v38 offset0:138 offset1:203
	s_waitcnt lgkmcnt(0)
	v_mul_f32_e32 v38, 0x42800000, v36
	v_cvt_pk_fp8_f32 v36, v39, v40
	v_mul_f32_e32 v37, 0x42800000, v37
	v_cvt_pk_fp8_f32 v36, v38, v37 op_sel:[0,0,1]
	v_add_u32_e32 v37, 0xc00, v81
	ds_read2_b32 v[38:39], v37 offset0:12 offset1:77
	s_waitcnt lgkmcnt(0)
	v_mul_f32_e32 v40, 0x42800000, v38
	v_mul_f32_e32 v41, 0x42800000, v39
	ds_read2_b32 v[38:39], v37 offset0:142 offset1:207
	v_cvt_pk_fp8_f32 v37, v40, v41
	s_waitcnt lgkmcnt(0)
	v_mul_f32_e32 v38, 0x42800000, v38
	v_mul_f32_e32 v39, 0x42800000, v39
	v_cvt_pk_fp8_f32 v37, v38, v39 op_sel:[0,0,1]
	v_lshl_add_u64 v[38:39], s[8:9], 0, v[88:89]
	v_lshl_add_u64 v[38:39], v[38:39], 0, v[86:87]
	global_store_dwordx4 v[38:39], v[34:37], off
	ds_read2_b32 v[34:35], v85 offset1:65
	s_waitcnt lgkmcnt(0)
	v_mul_f32_e32 v36, 0x42800000, v34
	v_mul_f32_e32 v37, 0x42800000, v35
	ds_read2_b32 v[34:35], v85 offset0:130 offset1:195
	s_waitcnt lgkmcnt(0)
	v_mul_f32_e32 v38, 0x42800000, v34
	v_cvt_pk_fp8_f32 v34, v36, v37
	v_mul_f32_e32 v35, 0x42800000, v35
	v_cvt_pk_fp8_f32 v34, v38, v35 op_sel:[0,0,1]
	v_add_u32_e32 v35, 0x400, v85
	ds_read2_b32 v[36:37], v35 offset0:4 offset1:69
	s_waitcnt lgkmcnt(0)
	v_mul_f32_e32 v38, 0x42800000, v36
	v_mul_f32_e32 v39, 0x42800000, v37
	ds_read2_b32 v[36:37], v35 offset0:134 offset1:199
	v_cvt_pk_fp8_f32 v35, v38, v39
	v_add_u32_e32 v38, 0x800, v85
	s_waitcnt lgkmcnt(0)
	v_mul_f32_e32 v36, 0x42800000, v36
	v_mul_f32_e32 v37, 0x42800000, v37
	v_cvt_pk_fp8_f32 v35, v36, v37 op_sel:[0,0,1]
	ds_read2_b32 v[36:37], v38 offset0:8 offset1:73
	s_waitcnt lgkmcnt(0)
	v_mul_f32_e32 v39, 0x42800000, v36
	v_mul_f32_e32 v40, 0x42800000, v37
	ds_read2_b32 v[36:37], v38 offset0:138 offset1:203
	s_waitcnt lgkmcnt(0)
	v_mul_f32_e32 v38, 0x42800000, v36
	v_cvt_pk_fp8_f32 v36, v39, v40
	v_mul_f32_e32 v37, 0x42800000, v37
	v_cvt_pk_fp8_f32 v36, v38, v37 op_sel:[0,0,1]
	v_add_u32_e32 v37, 0xc00, v85
	ds_read2_b32 v[38:39], v37 offset0:12 offset1:77
	s_waitcnt lgkmcnt(0)
	v_mul_f32_e32 v40, 0x42800000, v38
	v_mul_f32_e32 v41, 0x42800000, v39
	ds_read2_b32 v[38:39], v37 offset0:142 offset1:207
	v_cvt_pk_fp8_f32 v37, v40, v41
	s_waitcnt lgkmcnt(0)
	v_mul_f32_e32 v38, 0x42800000, v38
	v_mul_f32_e32 v39, 0x42800000, v39
	v_cvt_pk_fp8_f32 v37, v38, v39 op_sel:[0,0,1]
	s_branch .LBB0_539
